# latent mlstm_out row loop unrolled x2 with a second prefetch register set: rows fetched two iterations ahead
# speedup vs baseline: 1.0080x; 1.0080x over previous
.LBB0_844:
	s_or_b64 exec, exec, s[10:11]
	s_waitcnt vmcnt(0)
	v_mov_b32_e32 v18, v232
	s_waitcnt vmcnt(0) lgkmcnt(0)
	s_barrier
	s_nop 0
	v_ashrrev_i32_e32 v19, 6, v18
	v_cmp_gt_i32_e32 vcc, 64, v19
	s_and_saveexec_b64 s[10:11], vcc
	s_mov_b64 s[36:37], 0x4000
	s_mov_b64 s[40:41], 0x2200000
	s_cbranch_execz .LBB0_847
	s_load_dwordx2 s[14:15], s[44:45], 0x48
	v_readlane_b32 s26, v255, 32
	v_lshlrev_b32_e32 v1, 6, v18
	v_readlane_b32 s27, v255, 33
	v_and_b32_e32 v1, 0xfc0, v1
	s_waitcnt lgkmcnt(0)
	s_add_u32 s14, s14, s26
	s_addc_u32 s15, s15, s27
	global_load_dwordx4 v[2:5], v1, s[14:15]
	global_load_dwordx4 v[6:9], v1, s[14:15] offset:16
	global_load_dwordx4 v[10:13], v1, s[14:15] offset:32
	global_load_dwordx4 v[14:17], v1, s[14:15] offset:48
	v_readlane_b32 s6, v255, 30
	s_sub_i32 s6, s62, s6
	s_lshr_b32 s14, s6, 6
	s_lshl_b32 s6, s6, 6
	s_mul_i32 s15, s14, 0x1100
	s_and_b32 s6, s6, 0xfc0
	v_cmp_lt_i32_e32 vcc, v231, v225
	s_add_i32 s14, s15, s6
	s_and_b32 s6, s62, 63
	v_cndmask_b32_e32 v1, v223, v231, vcc
	v_cmp_lt_i32_e32 vcc, v230, v225
	s_lshl_b32 s6, s6, 6
	s_add_i32 s6, s6, s15
	v_cndmask_b32_e32 v20, v223, v230, vcc
	v_cmp_lt_i32_e32 vcc, v229, v225
	v_lshlrev_b32_e32 v26, 2, v20
	s_load_dwordx2 s[26:27], s[44:45], 0xb0
	v_cndmask_b32_e32 v20, v223, v229, vcc
	v_cmp_lt_i32_e32 vcc, v222, v225
	v_lshlrev_b32_e32 v27, 2, v20
	v_add_u32_e32 v19, s6, v19
	v_cndmask_b32_e32 v20, v223, v222, vcc
	v_lshlrev_b32_e32 v28, 2, v20
	v_add_u32_e32 v20, 0x100, v19
	v_ashrrev_i32_e32 v21, 31, v20
	v_lshlrev_b64 v[20:21], 11, v[20:21]
	v_and_b32_e32 v18, 63, v18
	v_lshl_or_b32 v20, v18, 5, v20
	v_add_u32_e32 v29, 0xf8, v19
	s_waitcnt lgkmcnt(0)
	v_lshl_add_u64 v[18:19], s[26:27], 0, v[20:21]
	s_mov_b64 s[26:27], 0x25610000
	v_lshlrev_b32_e32 v1, 2, v1
	s_addk_i32 s14, 0x138
	v_lshl_add_u64 v[18:19], v[18:19], 0, s[26:27]
	s_mov_b64 s[26:27], 0
	v_lshl_add_u64 v[62:63], v[18:19], 0, s[40:41]
	global_load_dwordx4 v[100:103], v[18:19], off offset:16
	global_load_dwordx4 v[104:107], v[18:19], off
	global_load_dwordx4 v[108:111], v[62:63], off
	global_load_dwordx4 v[112:115], v[62:63], off offset:16
	v_add_co_u32_e32 v64, vcc, s92, v18
	s_nop 1
	v_addc_co_u32_e32 v65, vcc, -1, v19, vcc
	global_load_dwordx4 v[116:119], v[64:65], off
	v_add_co_u32_e32 v64, vcc, s93, v18
	s_nop 1
	v_addc_co_u32_e32 v65, vcc, -1, v19, vcc
	global_load_dwordx4 v[120:123], v[64:65], off
	v_add_co_u32_e32 v64, vcc, s94, v18
	s_nop 1
	v_addc_co_u32_e32 v65, vcc, -1, v19, vcc
	global_load_dwordx4 v[124:127], v[64:65], off offset:-4080
	v_add_co_u32_e32 v64, vcc, s95, v18
	s_nop 1
	v_addc_co_u32_e32 v65, vcc, -1, v19, vcc
	global_load_dwordx4 v[128:131], v[64:65], off offset:-4080
	s_mov_b64 s[100:101], 0x8000
	v_lshl_add_u64 v[60:61], v[18:19], 0, s[36:37]
	v_lshl_add_u64 v[62:63], v[60:61], 0, s[40:41]
	global_load_dwordx4 v[148:151], v[60:61], off offset:16
	global_load_dwordx4 v[152:155], v[60:61], off
	global_load_dwordx4 v[156:159], v[62:63], off
	global_load_dwordx4 v[160:163], v[62:63], off offset:16
	v_add_co_u32_e32 v64, vcc, s92, v60
	s_nop 1
	v_addc_co_u32_e32 v65, vcc, -1, v61, vcc
	global_load_dwordx4 v[164:167], v[64:65], off
	v_add_co_u32_e32 v64, vcc, s93, v60
	s_nop 1
	v_addc_co_u32_e32 v65, vcc, -1, v61, vcc
	global_load_dwordx4 v[168:171], v[64:65], off
	v_add_co_u32_e32 v64, vcc, s94, v60
	s_nop 1
	v_addc_co_u32_e32 v65, vcc, -1, v61, vcc
	global_load_dwordx4 v[172:175], v[64:65], off offset:-4080
	v_add_co_u32_e32 v64, vcc, s95, v60
	s_nop 1
	v_addc_co_u32_e32 v65, vcc, -1, v61, vcc
	global_load_dwordx4 v[176:179], v[64:65], off offset:-4080
	s_waitcnt vmcnt(0)
.LBB0_846:
	s_waitcnt vmcnt(12)
	v_mov_b32_e32 v20, v100
	v_mov_b32_e32 v21, v101
	v_mov_b32_e32 v22, v102
	v_mov_b32_e32 v23, v103
	v_mov_b32_e32 v30, v104
	v_mov_b32_e32 v31, v105
	v_mov_b32_e32 v32, v106
	v_mov_b32_e32 v33, v107
	v_mov_b32_e32 v34, v108
	v_mov_b32_e32 v35, v109
	v_mov_b32_e32 v36, v110
	v_mov_b32_e32 v37, v111
	v_mov_b32_e32 v38, v112
	v_mov_b32_e32 v39, v113
	v_mov_b32_e32 v40, v114
	v_mov_b32_e32 v41, v115
	v_mov_b32_e32 v132, v116
	v_mov_b32_e32 v133, v117
	v_mov_b32_e32 v134, v118
	v_mov_b32_e32 v135, v119
	v_mov_b32_e32 v136, v120
	v_mov_b32_e32 v137, v121
	v_mov_b32_e32 v138, v122
	v_mov_b32_e32 v139, v123
	v_mov_b32_e32 v140, v124
	v_mov_b32_e32 v141, v125
	v_mov_b32_e32 v142, v126
	v_mov_b32_e32 v143, v127
	v_mov_b32_e32 v144, v128
	v_mov_b32_e32 v145, v129
	v_mov_b32_e32 v146, v130
	v_mov_b32_e32 v147, v131
	v_lshl_add_u64 v[60:61], v[18:19], 0, s[100:101]
	v_lshl_add_u64 v[62:63], v[60:61], 0, s[40:41]
	global_load_dwordx4 v[100:103], v[60:61], off offset:16
	global_load_dwordx4 v[104:107], v[60:61], off
	global_load_dwordx4 v[108:111], v[62:63], off
	global_load_dwordx4 v[112:115], v[62:63], off offset:16
	v_add_co_u32_e32 v64, vcc, s92, v60
	s_nop 1
	v_addc_co_u32_e32 v65, vcc, -1, v61, vcc
	global_load_dwordx4 v[116:119], v[64:65], off
	v_add_co_u32_e32 v64, vcc, s93, v60
	s_nop 1
	v_addc_co_u32_e32 v65, vcc, -1, v61, vcc
	global_load_dwordx4 v[120:123], v[64:65], off
	v_add_co_u32_e32 v64, vcc, s94, v60
	s_nop 1
	v_addc_co_u32_e32 v65, vcc, -1, v61, vcc
	global_load_dwordx4 v[124:127], v[64:65], off offset:-4080
	v_add_co_u32_e32 v64, vcc, s95, v60
	s_nop 1
	v_addc_co_u32_e32 v65, vcc, -1, v61, vcc
	global_load_dwordx4 v[128:131], v[64:65], off offset:-4080
	v_add_u32_e32 v29, 8, v29
	v_lshlrev_b32_e32 v25, 16, v30
	v_lshlrev_b32_e32 v24, 16, v34
	v_add_f32_e32 v44, v24, v25
	v_and_b32_e32 v24, 0xffff0000, v34
	v_and_b32_e32 v25, 0xffff0000, v30
	v_add_f32_e32 v45, v24, v25
	v_lshlrev_b32_e32 v24, 16, v35
	v_lshlrev_b32_e32 v25, 16, v31
	v_add_f32_e32 v46, v24, v25
	v_and_b32_e32 v24, 0xffff0000, v35
	v_and_b32_e32 v25, 0xffff0000, v31
	v_add_f32_e32 v47, v24, v25
	v_lshlrev_b32_e32 v24, 16, v36
	v_lshlrev_b32_e32 v25, 16, v32
	v_add_f32_e32 v48, v24, v25
	v_and_b32_e32 v24, 0xffff0000, v36
	v_and_b32_e32 v25, 0xffff0000, v32
	v_add_f32_e32 v49, v24, v25
	v_lshlrev_b32_e32 v24, 16, v37
	v_lshlrev_b32_e32 v25, 16, v33
	v_add_f32_e32 v50, v24, v25
	v_and_b32_e32 v24, 0xffff0000, v37
	v_and_b32_e32 v25, 0xffff0000, v33
	v_add_f32_e32 v51, v24, v25
	v_lshlrev_b32_e32 v24, 16, v20
	v_lshlrev_b32_e32 v25, 16, v38
	v_add_f32_e32 v31, v25, v24
	v_and_b32_e32 v24, 0xffff0000, v38
	v_and_b32_e32 v20, 0xffff0000, v20
	v_add_f32_e32 v30, v24, v20
	v_lshlrev_b32_e32 v25, 16, v21
	v_lshlrev_b32_e32 v33, 16, v39
	v_and_b32_e32 v32, 0xffff0000, v39
	v_and_b32_e32 v24, 0xffff0000, v21
	v_lshlrev_b32_e32 v21, 16, v22
	v_lshlrev_b32_e32 v35, 16, v40
	v_and_b32_e32 v34, 0xffff0000, v40
	v_and_b32_e32 v20, 0xffff0000, v22
	v_lshlrev_b32_e32 v37, 16, v23
	v_lshlrev_b32_e32 v39, 16, v41
	v_and_b32_e32 v38, 0xffff0000, v41
	v_and_b32_e32 v36, 0xffff0000, v23
	v_pk_add_f32 v[22:23], v[20:21], v[34:35]
	v_pk_add_f32 v[20:21], v[36:37], v[38:39]
	v_mul_f32_e32 v38, v44, v44
	v_fmac_f32_e32 v38, v45, v45
	v_fmac_f32_e32 v38, v46, v46
	v_fmac_f32_e32 v38, v47, v47
	v_fmac_f32_e32 v38, v48, v48
	v_fmac_f32_e32 v38, v49, v49
	v_fmac_f32_e32 v38, v50, v50
	v_fmac_f32_e32 v38, v51, v51
	v_pk_add_f32 v[24:25], v[24:25], v[32:33]
	v_fmac_f32_e32 v38, v31, v31
	v_pk_mul_f32 v[32:33], v[24:25], v[24:25]
	v_fmac_f32_e32 v38, v30, v30
	v_add_f32_e32 v33, v33, v38
	v_pk_mul_f32 v[34:35], v[22:23], v[22:23]
	v_add_f32_e32 v32, v32, v33
	v_add_f32_e32 v32, v35, v32
	v_pk_mul_f32 v[36:37], v[20:21], v[20:21]
	v_add_f32_e32 v32, v34, v32
	v_add_f32_e32 v32, v37, v32
	v_add_f32_e32 v32, v36, v32
	ds_bpermute_b32 v33, v1, v32
	s_waitcnt lgkmcnt(0)
	v_add_f32_e32 v32, v32, v33
	ds_bpermute_b32 v33, v26, v32
	s_waitcnt lgkmcnt(0)
	v_add_f32_e32 v32, v32, v33
	ds_bpermute_b32 v33, v27, v32
	s_waitcnt lgkmcnt(0)
	v_add_f32_e32 v32, v32, v33
	ds_bpermute_b32 v33, v28, v32
	s_waitcnt lgkmcnt(0)
	v_add_f32_e32 v32, v32, v33
	v_fmamk_f32 v32, v32, 0x3b800000, v234
	v_cmp_gt_f32_e32 vcc, s90, v32
	v_mul_f32_e32 v33, 0x4b800000, v32
	s_nop 0
	v_cndmask_b32_e32 v32, v32, v33, vcc
	v_rsq_f32_e32 v32, v32
	s_nop 0
	v_mul_f32_e32 v33, 0x45800000, v32
	v_cndmask_b32_e32 v32, v32, v33, vcc
	v_add_co_u32_e32 v42, vcc, s92, v18
	v_mul_f32_e32 v33, v44, v32
	s_nop 0
	v_addc_co_u32_e32 v43, vcc, -1, v19, vcc
	v_add_co_u32_e32 v38, vcc, s93, v18
	v_mov_b32_e32 v34, v132
	v_mov_b32_e32 v35, v133
	v_mov_b32_e32 v36, v134
	v_mov_b32_e32 v37, v135
	s_nop 0
	v_addc_co_u32_e32 v39, vcc, -1, v19, vcc
	v_mov_b32_e32 v38, v136
	v_mov_b32_e32 v39, v137
	v_mov_b32_e32 v40, v138
	v_mov_b32_e32 v41, v139
	v_mul_f32_e32 v33, v2, v33
	v_mul_f32_e32 v31, v31, v32
	v_mul_f32_e32 v31, v10, v31
	v_mul_f32_e32 v30, v30, v32
	v_mul_f32_e32 v30, v11, v30
	v_mul_f32_e32 v25, v25, v32
	v_mul_f32_e32 v25, v12, v25
	v_mul_f32_e32 v24, v24, v32
	v_mul_f32_e32 v24, v13, v24
	v_mul_f32_e32 v23, v23, v32
	v_mul_f32_e32 v23, v14, v23
	v_mul_f32_e32 v22, v22, v32
	v_mul_f32_e32 v22, v15, v22
	v_mul_f32_e32 v21, v21, v32
	v_mul_f32_e32 v21, v16, v21
	v_mul_f32_e32 v20, v20, v32
	v_mul_f32_e32 v20, v17, v20
	v_lshlrev_b32_e32 v44, 16, v34
	v_mul_f32_e32 v33, v33, v44
	v_and_b32_e32 v34, 0xffff0000, v34
	v_lshlrev_b32_e32 v44, 16, v38
	v_mul_f32_e32 v33, v33, v44
	v_mul_f32_e32 v44, v45, v32
	v_mul_f32_e32 v44, v3, v44
	v_mul_f32_e32 v34, v44, v34
	v_and_b32_e32 v38, 0xffff0000, v38
	v_mul_f32_e32 v34, v34, v38
	s_nop 1
	v_cvt_pk_bf16_f32 v34, v33, v34
	v_mul_f32_e32 v33, v46, v32
	v_mul_f32_e32 v33, v4, v33
	v_lshlrev_b32_e32 v38, 16, v35
	v_mul_f32_e32 v33, v33, v38
	v_lshlrev_b32_e32 v38, 16, v39
	v_mul_f32_e32 v33, v33, v38
	v_mul_f32_e32 v38, v47, v32
	v_mul_f32_e32 v38, v5, v38
	v_and_b32_e32 v35, 0xffff0000, v35
	v_mul_f32_e32 v35, v38, v35
	v_and_b32_e32 v38, 0xffff0000, v39
	v_mul_f32_e32 v35, v35, v38
	s_nop 1
	v_cvt_pk_bf16_f32 v35, v33, v35
	v_mul_f32_e32 v33, v48, v32
	v_mul_f32_e32 v33, v6, v33
	v_lshlrev_b32_e32 v38, 16, v36
	v_mul_f32_e32 v33, v33, v38
	v_lshlrev_b32_e32 v38, 16, v40
	v_mul_f32_e32 v33, v33, v38
	v_mul_f32_e32 v38, v49, v32
	v_mul_f32_e32 v38, v7, v38
	v_and_b32_e32 v36, 0xffff0000, v36
	v_mul_f32_e32 v36, v38, v36
	v_and_b32_e32 v38, 0xffff0000, v40
	v_mul_f32_e32 v36, v36, v38
	s_nop 1
	v_cvt_pk_bf16_f32 v36, v33, v36
	v_mul_f32_e32 v33, v50, v32
	v_mul_f32_e32 v33, v8, v33
	v_lshlrev_b32_e32 v38, 16, v37
	v_mul_f32_e32 v33, v33, v38
	v_lshlrev_b32_e32 v38, 16, v41
	v_mul_f32_e32 v33, v33, v38
	v_mul_f32_e32 v38, v51, v32
	v_mul_f32_e32 v38, v9, v38
	v_and_b32_e32 v37, 0xffff0000, v37
	v_mul_f32_e32 v37, v38, v37
	v_and_b32_e32 v38, 0xffff0000, v41
	v_mul_f32_e32 v37, v37, v38
	s_nop 1
	v_cvt_pk_bf16_f32 v37, v33, v37
	global_store_dwordx4 v[42:43], v[34:37], off
	v_add_co_u32_e32 v42, vcc, s94, v18
	s_nop 1
	v_addc_co_u32_e32 v43, vcc, -1, v19, vcc
	v_add_co_u32_e32 v38, vcc, s95, v18
	v_mov_b32_e32 v34, v140
	v_mov_b32_e32 v35, v141
	v_mov_b32_e32 v36, v142
	v_mov_b32_e32 v37, v143
	s_nop 0
	v_addc_co_u32_e32 v39, vcc, -1, v19, vcc
	v_mov_b32_e32 v38, v144
	v_mov_b32_e32 v39, v145
	v_mov_b32_e32 v40, v146
	v_mov_b32_e32 v41, v147
	v_cmp_le_i32_e32 vcc, s14, v29
	v_lshl_add_u64 v[18:19], v[18:19], 0, s[36:37]
	s_or_b64 s[26:27], vcc, s[26:27]
	v_lshlrev_b32_e32 v33, 16, v34
	v_mul_f32_e32 v31, v31, v33
	v_lshlrev_b32_e32 v33, 16, v38
	v_mul_f32_e32 v31, v31, v33
	v_and_b32_e32 v33, 0xffff0000, v34
	v_mul_f32_e32 v30, v30, v33
	v_and_b32_e32 v33, 0xffff0000, v38
	v_mul_f32_e32 v30, v30, v33
	s_nop 1
	v_cvt_pk_bf16_f32 v34, v31, v30
	v_lshlrev_b32_e32 v30, 16, v35
	v_mul_f32_e32 v25, v25, v30
	v_lshlrev_b32_e32 v30, 16, v39
	v_mul_f32_e32 v25, v25, v30
	v_and_b32_e32 v30, 0xffff0000, v35
	v_mul_f32_e32 v24, v24, v30
	v_and_b32_e32 v30, 0xffff0000, v39
	v_mul_f32_e32 v24, v24, v30
	s_nop 1
	v_cvt_pk_bf16_f32 v35, v25, v24
	v_lshlrev_b32_e32 v24, 16, v36
	v_mul_f32_e32 v23, v23, v24
	v_lshlrev_b32_e32 v24, 16, v40
	v_mul_f32_e32 v23, v23, v24
	v_and_b32_e32 v24, 0xffff0000, v36
	v_mul_f32_e32 v22, v22, v24
	v_and_b32_e32 v24, 0xffff0000, v40
	v_mul_f32_e32 v22, v22, v24
	s_nop 1
	v_cvt_pk_bf16_f32 v36, v23, v22
	v_lshlrev_b32_e32 v22, 16, v37
	v_mul_f32_e32 v21, v21, v22
	v_lshlrev_b32_e32 v22, 16, v41
	v_mul_f32_e32 v21, v21, v22
	v_and_b32_e32 v22, 0xffff0000, v37
	v_mul_f32_e32 v20, v20, v22
	v_and_b32_e32 v22, 0xffff0000, v41
	v_mul_f32_e32 v20, v20, v22
	s_nop 1
	v_cvt_pk_bf16_f32 v37, v21, v20
	global_store_dwordx4 v[42:43], v[34:37], off offset:-4080
	s_andn2_b64 exec, exec, s[26:27]
	s_cbranch_execz .LBB0_847
.Lmo_second:
	s_waitcnt vmcnt(12)
	v_mov_b32_e32 v20, v148
	v_mov_b32_e32 v21, v149
	v_mov_b32_e32 v22, v150
	v_mov_b32_e32 v23, v151
	v_mov_b32_e32 v30, v152
	v_mov_b32_e32 v31, v153
	v_mov_b32_e32 v32, v154
	v_mov_b32_e32 v33, v155
	v_mov_b32_e32 v34, v156
	v_mov_b32_e32 v35, v157
	v_mov_b32_e32 v36, v158
	v_mov_b32_e32 v37, v159
	v_mov_b32_e32 v38, v160
	v_mov_b32_e32 v39, v161
	v_mov_b32_e32 v40, v162
	v_mov_b32_e32 v41, v163
	v_mov_b32_e32 v132, v164
	v_mov_b32_e32 v133, v165
	v_mov_b32_e32 v134, v166
	v_mov_b32_e32 v135, v167
	v_mov_b32_e32 v136, v168
	v_mov_b32_e32 v137, v169
	v_mov_b32_e32 v138, v170
	v_mov_b32_e32 v139, v171
	v_mov_b32_e32 v140, v172
	v_mov_b32_e32 v141, v173
	v_mov_b32_e32 v142, v174
	v_mov_b32_e32 v143, v175
	v_mov_b32_e32 v144, v176
	v_mov_b32_e32 v145, v177
	v_mov_b32_e32 v146, v178
	v_mov_b32_e32 v147, v179
	v_lshl_add_u64 v[60:61], v[18:19], 0, s[100:101]
	v_lshl_add_u64 v[62:63], v[60:61], 0, s[40:41]
	global_load_dwordx4 v[148:151], v[60:61], off offset:16
	global_load_dwordx4 v[152:155], v[60:61], off
	global_load_dwordx4 v[156:159], v[62:63], off
	global_load_dwordx4 v[160:163], v[62:63], off offset:16
	v_add_co_u32_e32 v64, vcc, s92, v60
	s_nop 1
	v_addc_co_u32_e32 v65, vcc, -1, v61, vcc
	global_load_dwordx4 v[164:167], v[64:65], off
	v_add_co_u32_e32 v64, vcc, s93, v60
	s_nop 1
	v_addc_co_u32_e32 v65, vcc, -1, v61, vcc
	global_load_dwordx4 v[168:171], v[64:65], off
	v_add_co_u32_e32 v64, vcc, s94, v60
	s_nop 1
	v_addc_co_u32_e32 v65, vcc, -1, v61, vcc
	global_load_dwordx4 v[172:175], v[64:65], off offset:-4080
	v_add_co_u32_e32 v64, vcc, s95, v60
	s_nop 1
	v_addc_co_u32_e32 v65, vcc, -1, v61, vcc
	global_load_dwordx4 v[176:179], v[64:65], off offset:-4080
	v_add_u32_e32 v29, 8, v29
	v_lshlrev_b32_e32 v25, 16, v30
	v_lshlrev_b32_e32 v24, 16, v34
	v_add_f32_e32 v44, v24, v25
	v_and_b32_e32 v24, 0xffff0000, v34
	v_and_b32_e32 v25, 0xffff0000, v30
	v_add_f32_e32 v45, v24, v25
	v_lshlrev_b32_e32 v24, 16, v35
	v_lshlrev_b32_e32 v25, 16, v31
	v_add_f32_e32 v46, v24, v25
	v_and_b32_e32 v24, 0xffff0000, v35
	v_and_b32_e32 v25, 0xffff0000, v31
	v_add_f32_e32 v47, v24, v25
	v_lshlrev_b32_e32 v24, 16, v36
	v_lshlrev_b32_e32 v25, 16, v32
	v_add_f32_e32 v48, v24, v25
	v_and_b32_e32 v24, 0xffff0000, v36
	v_and_b32_e32 v25, 0xffff0000, v32
	v_add_f32_e32 v49, v24, v25
	v_lshlrev_b32_e32 v24, 16, v37
	v_lshlrev_b32_e32 v25, 16, v33
	v_add_f32_e32 v50, v24, v25
	v_and_b32_e32 v24, 0xffff0000, v37
	v_and_b32_e32 v25, 0xffff0000, v33
	v_add_f32_e32 v51, v24, v25
	v_lshlrev_b32_e32 v24, 16, v20
	v_lshlrev_b32_e32 v25, 16, v38
	v_add_f32_e32 v31, v25, v24
	v_and_b32_e32 v24, 0xffff0000, v38
	v_and_b32_e32 v20, 0xffff0000, v20
	v_add_f32_e32 v30, v24, v20
	v_lshlrev_b32_e32 v25, 16, v21
	v_lshlrev_b32_e32 v33, 16, v39
	v_and_b32_e32 v32, 0xffff0000, v39
	v_and_b32_e32 v24, 0xffff0000, v21
	v_lshlrev_b32_e32 v21, 16, v22
	v_lshlrev_b32_e32 v35, 16, v40
	v_and_b32_e32 v34, 0xffff0000, v40
	v_and_b32_e32 v20, 0xffff0000, v22
	v_lshlrev_b32_e32 v37, 16, v23
	v_lshlrev_b32_e32 v39, 16, v41
	v_and_b32_e32 v38, 0xffff0000, v41
	v_and_b32_e32 v36, 0xffff0000, v23
	v_pk_add_f32 v[22:23], v[20:21], v[34:35]
	v_pk_add_f32 v[20:21], v[36:37], v[38:39]
	v_mul_f32_e32 v38, v44, v44
	v_fmac_f32_e32 v38, v45, v45
	v_fmac_f32_e32 v38, v46, v46
	v_fmac_f32_e32 v38, v47, v47
	v_fmac_f32_e32 v38, v48, v48
	v_fmac_f32_e32 v38, v49, v49
	v_fmac_f32_e32 v38, v50, v50
	v_fmac_f32_e32 v38, v51, v51
	v_pk_add_f32 v[24:25], v[24:25], v[32:33]
	v_fmac_f32_e32 v38, v31, v31
	v_pk_mul_f32 v[32:33], v[24:25], v[24:25]
	v_fmac_f32_e32 v38, v30, v30
	v_add_f32_e32 v33, v33, v38
	v_pk_mul_f32 v[34:35], v[22:23], v[22:23]
	v_add_f32_e32 v32, v32, v33
	v_add_f32_e32 v32, v35, v32
	v_pk_mul_f32 v[36:37], v[20:21], v[20:21]
	v_add_f32_e32 v32, v34, v32
	v_add_f32_e32 v32, v37, v32
	v_add_f32_e32 v32, v36, v32
	ds_bpermute_b32 v33, v1, v32
	s_waitcnt lgkmcnt(0)
	v_add_f32_e32 v32, v32, v33
	ds_bpermute_b32 v33, v26, v32
	s_waitcnt lgkmcnt(0)
	v_add_f32_e32 v32, v32, v33
	ds_bpermute_b32 v33, v27, v32
	s_waitcnt lgkmcnt(0)
	v_add_f32_e32 v32, v32, v33
	ds_bpermute_b32 v33, v28, v32
	s_waitcnt lgkmcnt(0)
	v_add_f32_e32 v32, v32, v33
	v_fmamk_f32 v32, v32, 0x3b800000, v234
	v_cmp_gt_f32_e32 vcc, s90, v32
	v_mul_f32_e32 v33, 0x4b800000, v32
	s_nop 0
	v_cndmask_b32_e32 v32, v32, v33, vcc
	v_rsq_f32_e32 v32, v32
	s_nop 0
	v_mul_f32_e32 v33, 0x45800000, v32
	v_cndmask_b32_e32 v32, v32, v33, vcc
	v_add_co_u32_e32 v42, vcc, s92, v18
	v_mul_f32_e32 v33, v44, v32
	s_nop 0
	v_addc_co_u32_e32 v43, vcc, -1, v19, vcc
	v_add_co_u32_e32 v38, vcc, s93, v18
	v_mov_b32_e32 v34, v132
	v_mov_b32_e32 v35, v133
	v_mov_b32_e32 v36, v134
	v_mov_b32_e32 v37, v135
	s_nop 0
	v_addc_co_u32_e32 v39, vcc, -1, v19, vcc
	v_mov_b32_e32 v38, v136
	v_mov_b32_e32 v39, v137
	v_mov_b32_e32 v40, v138
	v_mov_b32_e32 v41, v139
	v_mul_f32_e32 v33, v2, v33
	v_mul_f32_e32 v31, v31, v32
	v_mul_f32_e32 v31, v10, v31
	v_mul_f32_e32 v30, v30, v32
	v_mul_f32_e32 v30, v11, v30
	v_mul_f32_e32 v25, v25, v32
	v_mul_f32_e32 v25, v12, v25
	v_mul_f32_e32 v24, v24, v32
	v_mul_f32_e32 v24, v13, v24
	v_mul_f32_e32 v23, v23, v32
	v_mul_f32_e32 v23, v14, v23
	v_mul_f32_e32 v22, v22, v32
	v_mul_f32_e32 v22, v15, v22
	v_mul_f32_e32 v21, v21, v32
	v_mul_f32_e32 v21, v16, v21
	v_mul_f32_e32 v20, v20, v32
	v_mul_f32_e32 v20, v17, v20
	v_lshlrev_b32_e32 v44, 16, v34
	v_mul_f32_e32 v33, v33, v44
	v_and_b32_e32 v34, 0xffff0000, v34
	v_lshlrev_b32_e32 v44, 16, v38
	v_mul_f32_e32 v33, v33, v44
	v_mul_f32_e32 v44, v45, v32
	v_mul_f32_e32 v44, v3, v44
	v_mul_f32_e32 v34, v44, v34
	v_and_b32_e32 v38, 0xffff0000, v38
	v_mul_f32_e32 v34, v34, v38
	s_nop 1
	v_cvt_pk_bf16_f32 v34, v33, v34
	v_mul_f32_e32 v33, v46, v32
	v_mul_f32_e32 v33, v4, v33
	v_lshlrev_b32_e32 v38, 16, v35
	v_mul_f32_e32 v33, v33, v38
	v_lshlrev_b32_e32 v38, 16, v39
	v_mul_f32_e32 v33, v33, v38
	v_mul_f32_e32 v38, v47, v32
	v_mul_f32_e32 v38, v5, v38
	v_and_b32_e32 v35, 0xffff0000, v35
	v_mul_f32_e32 v35, v38, v35
	v_and_b32_e32 v38, 0xffff0000, v39
	v_mul_f32_e32 v35, v35, v38
	s_nop 1
	v_cvt_pk_bf16_f32 v35, v33, v35
	v_mul_f32_e32 v33, v48, v32
	v_mul_f32_e32 v33, v6, v33
	v_lshlrev_b32_e32 v38, 16, v36
	v_mul_f32_e32 v33, v33, v38
	v_lshlrev_b32_e32 v38, 16, v40
	v_mul_f32_e32 v33, v33, v38
	v_mul_f32_e32 v38, v49, v32
	v_mul_f32_e32 v38, v7, v38
	v_and_b32_e32 v36, 0xffff0000, v36
	v_mul_f32_e32 v36, v38, v36
	v_and_b32_e32 v38, 0xffff0000, v40
	v_mul_f32_e32 v36, v36, v38
	s_nop 1
	v_cvt_pk_bf16_f32 v36, v33, v36
	v_mul_f32_e32 v33, v50, v32
	v_mul_f32_e32 v33, v8, v33
	v_lshlrev_b32_e32 v38, 16, v37
	v_mul_f32_e32 v33, v33, v38
	v_lshlrev_b32_e32 v38, 16, v41
	v_mul_f32_e32 v33, v33, v38
	v_mul_f32_e32 v38, v51, v32
	v_mul_f32_e32 v38, v9, v38
	v_and_b32_e32 v37, 0xffff0000, v37
	v_mul_f32_e32 v37, v38, v37
	v_and_b32_e32 v38, 0xffff0000, v41
	v_mul_f32_e32 v37, v37, v38
	s_nop 1
	v_cvt_pk_bf16_f32 v37, v33, v37
	global_store_dwordx4 v[42:43], v[34:37], off
	v_add_co_u32_e32 v42, vcc, s94, v18
	s_nop 1
	v_addc_co_u32_e32 v43, vcc, -1, v19, vcc
	v_add_co_u32_e32 v38, vcc, s95, v18
	v_mov_b32_e32 v34, v140
	v_mov_b32_e32 v35, v141
	v_mov_b32_e32 v36, v142
	v_mov_b32_e32 v37, v143
	s_nop 0
	v_addc_co_u32_e32 v39, vcc, -1, v19, vcc
	v_mov_b32_e32 v38, v144
	v_mov_b32_e32 v39, v145
	v_mov_b32_e32 v40, v146
	v_mov_b32_e32 v41, v147
	v_cmp_le_i32_e32 vcc, s14, v29
	v_lshl_add_u64 v[18:19], v[18:19], 0, s[36:37]
	s_or_b64 s[26:27], vcc, s[26:27]
	v_lshlrev_b32_e32 v33, 16, v34
	v_mul_f32_e32 v31, v31, v33
	v_lshlrev_b32_e32 v33, 16, v38
	v_mul_f32_e32 v31, v31, v33
	v_and_b32_e32 v33, 0xffff0000, v34
	v_mul_f32_e32 v30, v30, v33
	v_and_b32_e32 v33, 0xffff0000, v38
	v_mul_f32_e32 v30, v30, v33
	s_nop 1
	v_cvt_pk_bf16_f32 v34, v31, v30
	v_lshlrev_b32_e32 v30, 16, v35
	v_mul_f32_e32 v25, v25, v30
	v_lshlrev_b32_e32 v30, 16, v39
	v_mul_f32_e32 v25, v25, v30
	v_and_b32_e32 v30, 0xffff0000, v35
	v_mul_f32_e32 v24, v24, v30
	v_and_b32_e32 v30, 0xffff0000, v39
	v_mul_f32_e32 v24, v24, v30
	s_nop 1
	v_cvt_pk_bf16_f32 v35, v25, v24
	v_lshlrev_b32_e32 v24, 16, v36
	v_mul_f32_e32 v23, v23, v24
	v_lshlrev_b32_e32 v24, 16, v40
	v_mul_f32_e32 v23, v23, v24
	v_and_b32_e32 v24, 0xffff0000, v36
	v_mul_f32_e32 v22, v22, v24
	v_and_b32_e32 v24, 0xffff0000, v40
	v_mul_f32_e32 v22, v22, v24
	s_nop 1
	v_cvt_pk_bf16_f32 v36, v23, v22
	v_lshlrev_b32_e32 v22, 16, v37
	v_mul_f32_e32 v21, v21, v22
	v_lshlrev_b32_e32 v22, 16, v41
	v_mul_f32_e32 v21, v21, v22
	v_and_b32_e32 v22, 0xffff0000, v37
	v_mul_f32_e32 v20, v20, v22
	v_and_b32_e32 v22, 0xffff0000, v41
	v_mul_f32_e32 v20, v20, v22
	s_nop 1
	v_cvt_pk_bf16_f32 v37, v21, v20
	global_store_dwordx4 v[42:43], v[34:37], off offset:-4080
	s_andn2_b64 exec, exec, s[26:27]
	s_cbranch_execnz .LBB0_846
